# v083 + P7: trailing half runs its SwiGLU epilogue at s_setprio 3 (back to 0 after the last store); leading half unchanged
# speedup vs baseline: 1.0047x; 1.0047x over previous
.Lp7_kloop_done:
.LBB0_796:
	s_and_b64 vcc, exec, s[24:25]
	s_cbranch_vccnz .Lp7_epi_prio_done
	s_setprio 3

.Lp7_epi_cached:
	v_mad_i64_i32 v[160:161], s[42:43], v148, s51, v[144:145]
	v_lshlrev_b64 v[146:147], 1, v[146:147]
	s_mov_b32 s66, 0x2c000
	s_mov_b32 s67, 0
	v_lshl_add_u64 v[160:161], v[160:161], 0, v[146:147]
	v_rsq_f32_e32 v176, v241
	v_pk_mul_f32 v[116:117], v[124:125], v[116:117]
	v_pk_mul_f32 v[118:119], v[126:127], v[118:119]
	v_pk_mul_f32 v[112:113], v[120:121], v[112:113]
	v_pk_mul_f32 v[114:115], v[122:123], v[114:115]
	v_mul_f32_e32 v177, 0xbfb8aa3b, v176
	v_mul_f32_e32 v162, v177, v124
	v_mul_f32_e32 v163, v177, v125
	v_mul_f32_e32 v164, v177, v126
	v_mul_f32_e32 v165, v177, v127
	v_mul_f32_e32 v166, v177, v120
	v_mul_f32_e32 v167, v177, v121
	v_mul_f32_e32 v168, v177, v122
	v_mul_f32_e32 v169, v177, v123
	v_exp_f32_e32 v162, v162
	v_exp_f32_e32 v163, v163
	v_exp_f32_e32 v164, v164
	v_exp_f32_e32 v165, v165
	v_exp_f32_e32 v166, v166
	v_exp_f32_e32 v167, v167
	v_exp_f32_e32 v168, v168
	v_exp_f32_e32 v169, v169
	v_fma_f32 v162, v162, v241, v241
	v_fma_f32 v163, v163, v241, v241
	v_fma_f32 v164, v164, v241, v241
	v_fma_f32 v165, v165, v241, v241
	v_fma_f32 v166, v166, v241, v241
	v_fma_f32 v167, v167, v241, v241
	v_fma_f32 v168, v168, v241, v241
	v_fma_f32 v169, v169, v241, v241
	v_rcp_f32_e32 v162, v162
	v_rcp_f32_e32 v163, v163
	v_rcp_f32_e32 v164, v164
	v_rcp_f32_e32 v165, v165
	v_rcp_f32_e32 v166, v166
	v_rcp_f32_e32 v167, v167
	v_rcp_f32_e32 v168, v168
	v_rcp_f32_e32 v169, v169
	v_pk_mul_f32 v[116:117], v[116:117], v[162:163]
	v_pk_mul_f32 v[118:119], v[118:119], v[164:165]
	v_pk_mul_f32 v[112:113], v[112:113], v[166:167]
	v_pk_mul_f32 v[114:115], v[114:115], v[168:169]
	v_cvt_pk_bf16_f32 v170, v116, v117
	v_cvt_pk_bf16_f32 v171, v118, v119
	v_cvt_pk_bf16_f32 v172, v112, v113
	v_cvt_pk_bf16_f32 v173, v114, v115
	global_store_dwordx4 v[160:161], v[170:173], off
	v_lshl_add_u64 v[160:161], v[160:161], 0, s[66:67]
	v_rsq_f32_e32 v176, v242
	v_pk_mul_f32 v[100:101], v[108:109], v[100:101]
	v_pk_mul_f32 v[102:103], v[110:111], v[102:103]
	v_pk_mul_f32 v[96:97], v[104:105], v[96:97]
	v_pk_mul_f32 v[98:99], v[106:107], v[98:99]
	v_mul_f32_e32 v177, 0xbfb8aa3b, v176
	v_mul_f32_e32 v162, v177, v108
	v_mul_f32_e32 v163, v177, v109
	v_mul_f32_e32 v164, v177, v110
	v_mul_f32_e32 v165, v177, v111
	v_mul_f32_e32 v166, v177, v104
	v_mul_f32_e32 v167, v177, v105
	v_mul_f32_e32 v168, v177, v106
	v_mul_f32_e32 v169, v177, v107
	v_exp_f32_e32 v162, v162
	v_exp_f32_e32 v163, v163
	v_exp_f32_e32 v164, v164
	v_exp_f32_e32 v165, v165
	v_exp_f32_e32 v166, v166
	v_exp_f32_e32 v167, v167
	v_exp_f32_e32 v168, v168
	v_exp_f32_e32 v169, v169
	v_fma_f32 v162, v162, v242, v242
	v_fma_f32 v163, v163, v242, v242
	v_fma_f32 v164, v164, v242, v242
	v_fma_f32 v165, v165, v242, v242
	v_fma_f32 v166, v166, v242, v242
	v_fma_f32 v167, v167, v242, v242
	v_fma_f32 v168, v168, v242, v242
	v_fma_f32 v169, v169, v242, v242
	v_rcp_f32_e32 v162, v162
	v_rcp_f32_e32 v163, v163
	v_rcp_f32_e32 v164, v164
	v_rcp_f32_e32 v165, v165
	v_rcp_f32_e32 v166, v166
	v_rcp_f32_e32 v167, v167
	v_rcp_f32_e32 v168, v168
	v_rcp_f32_e32 v169, v169
	v_pk_mul_f32 v[100:101], v[100:101], v[162:163]
	v_pk_mul_f32 v[102:103], v[102:103], v[164:165]
	v_pk_mul_f32 v[96:97], v[96:97], v[166:167]
	v_pk_mul_f32 v[98:99], v[98:99], v[168:169]
	v_cvt_pk_bf16_f32 v170, v100, v101
	v_cvt_pk_bf16_f32 v171, v102, v103
	v_cvt_pk_bf16_f32 v172, v96, v97
	v_cvt_pk_bf16_f32 v173, v98, v99
	global_store_dwordx4 v[160:161], v[170:173], off
	v_lshl_add_u64 v[160:161], v[160:161], 0, s[66:67]
	v_rsq_f32_e32 v176, v243
	v_pk_mul_f32 v[84:85], v[92:93], v[84:85]
	v_pk_mul_f32 v[86:87], v[94:95], v[86:87]
	v_pk_mul_f32 v[80:81], v[88:89], v[80:81]
	v_pk_mul_f32 v[82:83], v[90:91], v[82:83]
	v_mul_f32_e32 v177, 0xbfb8aa3b, v176
	v_mul_f32_e32 v162, v177, v92
	v_mul_f32_e32 v163, v177, v93
	v_mul_f32_e32 v164, v177, v94
	v_mul_f32_e32 v165, v177, v95
	v_mul_f32_e32 v166, v177, v88
	v_mul_f32_e32 v167, v177, v89
	v_mul_f32_e32 v168, v177, v90
	v_mul_f32_e32 v169, v177, v91
	v_exp_f32_e32 v162, v162
	v_exp_f32_e32 v163, v163
	v_exp_f32_e32 v164, v164
	v_exp_f32_e32 v165, v165
	v_exp_f32_e32 v166, v166
	v_exp_f32_e32 v167, v167
	v_exp_f32_e32 v168, v168
	v_exp_f32_e32 v169, v169
	v_fma_f32 v162, v162, v243, v243
	v_fma_f32 v163, v163, v243, v243
	v_fma_f32 v164, v164, v243, v243
	v_fma_f32 v165, v165, v243, v243
	v_fma_f32 v166, v166, v243, v243
	v_fma_f32 v167, v167, v243, v243
	v_fma_f32 v168, v168, v243, v243
	v_fma_f32 v169, v169, v243, v243
	v_rcp_f32_e32 v162, v162
	v_rcp_f32_e32 v163, v163
	v_rcp_f32_e32 v164, v164
	v_rcp_f32_e32 v165, v165
	v_rcp_f32_e32 v166, v166
	v_rcp_f32_e32 v167, v167
	v_rcp_f32_e32 v168, v168
	v_rcp_f32_e32 v169, v169
	v_pk_mul_f32 v[84:85], v[84:85], v[162:163]
	v_pk_mul_f32 v[86:87], v[86:87], v[164:165]
	v_pk_mul_f32 v[80:81], v[80:81], v[166:167]
	v_pk_mul_f32 v[82:83], v[82:83], v[168:169]
	v_cvt_pk_bf16_f32 v170, v84, v85
	v_cvt_pk_bf16_f32 v171, v86, v87
	v_cvt_pk_bf16_f32 v172, v80, v81
	v_cvt_pk_bf16_f32 v173, v82, v83
	global_store_dwordx4 v[160:161], v[170:173], off
	v_lshl_add_u64 v[160:161], v[160:161], 0, s[66:67]
	v_rsq_f32_e32 v176, v244
	v_pk_mul_f32 v[68:69], v[76:77], v[68:69]
	v_pk_mul_f32 v[70:71], v[78:79], v[70:71]
	v_pk_mul_f32 v[64:65], v[72:73], v[64:65]
	v_pk_mul_f32 v[66:67], v[74:75], v[66:67]
	v_mul_f32_e32 v177, 0xbfb8aa3b, v176
	v_mul_f32_e32 v162, v177, v76
	v_mul_f32_e32 v163, v177, v77
	v_mul_f32_e32 v164, v177, v78
	v_mul_f32_e32 v165, v177, v79
	v_mul_f32_e32 v166, v177, v72
	v_mul_f32_e32 v167, v177, v73
	v_mul_f32_e32 v168, v177, v74
	v_mul_f32_e32 v169, v177, v75
	v_exp_f32_e32 v162, v162
	v_exp_f32_e32 v163, v163
	v_exp_f32_e32 v164, v164
	v_exp_f32_e32 v165, v165
	v_exp_f32_e32 v166, v166
	v_exp_f32_e32 v167, v167
	v_exp_f32_e32 v168, v168
	v_exp_f32_e32 v169, v169
	v_fma_f32 v162, v162, v244, v244
	v_fma_f32 v163, v163, v244, v244
	v_fma_f32 v164, v164, v244, v244
	v_fma_f32 v165, v165, v244, v244
	v_fma_f32 v166, v166, v244, v244
	v_fma_f32 v167, v167, v244, v244
	v_fma_f32 v168, v168, v244, v244
	v_fma_f32 v169, v169, v244, v244
	v_rcp_f32_e32 v162, v162
	v_rcp_f32_e32 v163, v163
	v_rcp_f32_e32 v164, v164
	v_rcp_f32_e32 v165, v165
	v_rcp_f32_e32 v166, v166
	v_rcp_f32_e32 v167, v167
	v_rcp_f32_e32 v168, v168
	v_rcp_f32_e32 v169, v169
	v_pk_mul_f32 v[68:69], v[68:69], v[162:163]
	v_pk_mul_f32 v[70:71], v[70:71], v[164:165]
	v_pk_mul_f32 v[64:65], v[64:65], v[166:167]
	v_pk_mul_f32 v[66:67], v[66:67], v[168:169]
	v_cvt_pk_bf16_f32 v170, v68, v69
	v_cvt_pk_bf16_f32 v171, v70, v71
	v_cvt_pk_bf16_f32 v172, v64, v65
	v_cvt_pk_bf16_f32 v173, v66, v67
	global_store_dwordx4 v[160:161], v[170:173], off
	s_mov_b32 s66, 0xdc000
	v_lshl_add_u64 v[160:161], v[160:161], 0, s[66:67]
	v_rsq_f32_e32 v176, v245
	v_pk_mul_f32 v[52:53], v[60:61], v[52:53]
	v_pk_mul_f32 v[54:55], v[62:63], v[54:55]
	v_pk_mul_f32 v[48:49], v[56:57], v[48:49]
	v_pk_mul_f32 v[50:51], v[58:59], v[50:51]
	v_mul_f32_e32 v177, 0xbfb8aa3b, v176
	v_mul_f32_e32 v162, v177, v60
	v_mul_f32_e32 v163, v177, v61
	v_mul_f32_e32 v164, v177, v62
	v_mul_f32_e32 v165, v177, v63
	v_mul_f32_e32 v166, v177, v56
	v_mul_f32_e32 v167, v177, v57
	v_mul_f32_e32 v168, v177, v58
	v_mul_f32_e32 v169, v177, v59
	v_exp_f32_e32 v162, v162
	v_exp_f32_e32 v163, v163
	v_exp_f32_e32 v164, v164
	v_exp_f32_e32 v165, v165
	v_exp_f32_e32 v166, v166
	v_exp_f32_e32 v167, v167
	v_exp_f32_e32 v168, v168
	v_exp_f32_e32 v169, v169
	v_fma_f32 v162, v162, v245, v245
	v_fma_f32 v163, v163, v245, v245
	v_fma_f32 v164, v164, v245, v245
	v_fma_f32 v165, v165, v245, v245
	v_fma_f32 v166, v166, v245, v245
	v_fma_f32 v167, v167, v245, v245
	v_fma_f32 v168, v168, v245, v245
	v_fma_f32 v169, v169, v245, v245
	v_rcp_f32_e32 v162, v162
	v_rcp_f32_e32 v163, v163
	v_rcp_f32_e32 v164, v164
	v_rcp_f32_e32 v165, v165
	v_rcp_f32_e32 v166, v166
	v_rcp_f32_e32 v167, v167
	v_rcp_f32_e32 v168, v168
	v_rcp_f32_e32 v169, v169
	v_pk_mul_f32 v[52:53], v[52:53], v[162:163]
	v_pk_mul_f32 v[54:55], v[54:55], v[164:165]
	v_pk_mul_f32 v[48:49], v[48:49], v[166:167]
	v_pk_mul_f32 v[50:51], v[50:51], v[168:169]
	v_cvt_pk_bf16_f32 v170, v52, v53
	v_cvt_pk_bf16_f32 v171, v54, v55
	v_cvt_pk_bf16_f32 v172, v48, v49
	v_cvt_pk_bf16_f32 v173, v50, v51
	global_store_dwordx4 v[160:161], v[170:173], off
	s_mov_b32 s66, 0x2c000
	v_lshl_add_u64 v[160:161], v[160:161], 0, s[66:67]
	v_rsq_f32_e32 v176, v246
	v_pk_mul_f32 v[36:37], v[44:45], v[36:37]
	v_pk_mul_f32 v[38:39], v[46:47], v[38:39]
	v_pk_mul_f32 v[32:33], v[40:41], v[32:33]
	v_pk_mul_f32 v[34:35], v[42:43], v[34:35]
	v_mul_f32_e32 v177, 0xbfb8aa3b, v176
	v_mul_f32_e32 v162, v177, v44
	v_mul_f32_e32 v163, v177, v45
	v_mul_f32_e32 v164, v177, v46
	v_mul_f32_e32 v165, v177, v47
	v_mul_f32_e32 v166, v177, v40
	v_mul_f32_e32 v167, v177, v41
	v_mul_f32_e32 v168, v177, v42
	v_mul_f32_e32 v169, v177, v43
	v_exp_f32_e32 v162, v162
	v_exp_f32_e32 v163, v163
	v_exp_f32_e32 v164, v164
	v_exp_f32_e32 v165, v165
	v_exp_f32_e32 v166, v166
	v_exp_f32_e32 v167, v167
	v_exp_f32_e32 v168, v168
	v_exp_f32_e32 v169, v169
	v_fma_f32 v162, v162, v246, v246
	v_fma_f32 v163, v163, v246, v246
	v_fma_f32 v164, v164, v246, v246
	v_fma_f32 v165, v165, v246, v246
	v_fma_f32 v166, v166, v246, v246
	v_fma_f32 v167, v167, v246, v246
	v_fma_f32 v168, v168, v246, v246
	v_fma_f32 v169, v169, v246, v246
	v_rcp_f32_e32 v162, v162
	v_rcp_f32_e32 v163, v163
	v_rcp_f32_e32 v164, v164
	v_rcp_f32_e32 v165, v165
	v_rcp_f32_e32 v166, v166
	v_rcp_f32_e32 v167, v167
	v_rcp_f32_e32 v168, v168
	v_rcp_f32_e32 v169, v169
	v_pk_mul_f32 v[36:37], v[36:37], v[162:163]
	v_pk_mul_f32 v[38:39], v[38:39], v[164:165]
	v_pk_mul_f32 v[32:33], v[32:33], v[166:167]
	v_pk_mul_f32 v[34:35], v[34:35], v[168:169]
	v_cvt_pk_bf16_f32 v170, v36, v37
	v_cvt_pk_bf16_f32 v171, v38, v39
	v_cvt_pk_bf16_f32 v172, v32, v33
	v_cvt_pk_bf16_f32 v173, v34, v35
	global_store_dwordx4 v[160:161], v[170:173], off
	v_lshl_add_u64 v[160:161], v[160:161], 0, s[66:67]
	v_rsq_f32_e32 v176, v247
	v_pk_mul_f32 v[20:21], v[28:29], v[20:21]
	v_pk_mul_f32 v[22:23], v[30:31], v[22:23]
	v_pk_mul_f32 v[16:17], v[24:25], v[16:17]
	v_pk_mul_f32 v[18:19], v[26:27], v[18:19]
	v_mul_f32_e32 v177, 0xbfb8aa3b, v176
	v_mul_f32_e32 v162, v177, v28
	v_mul_f32_e32 v163, v177, v29
	v_mul_f32_e32 v164, v177, v30
	v_mul_f32_e32 v165, v177, v31
	v_mul_f32_e32 v166, v177, v24
	v_mul_f32_e32 v167, v177, v25
	v_mul_f32_e32 v168, v177, v26
	v_mul_f32_e32 v169, v177, v27
	v_exp_f32_e32 v162, v162
	v_exp_f32_e32 v163, v163
	v_exp_f32_e32 v164, v164
	v_exp_f32_e32 v165, v165
	v_exp_f32_e32 v166, v166
	v_exp_f32_e32 v167, v167
	v_exp_f32_e32 v168, v168
	v_exp_f32_e32 v169, v169
	v_fma_f32 v162, v162, v247, v247
	v_fma_f32 v163, v163, v247, v247
	v_fma_f32 v164, v164, v247, v247
	v_fma_f32 v165, v165, v247, v247
	v_fma_f32 v166, v166, v247, v247
	v_fma_f32 v167, v167, v247, v247
	v_fma_f32 v168, v168, v247, v247
	v_fma_f32 v169, v169, v247, v247
	v_rcp_f32_e32 v162, v162
	v_rcp_f32_e32 v163, v163
	v_rcp_f32_e32 v164, v164
	v_rcp_f32_e32 v165, v165
	v_rcp_f32_e32 v166, v166
	v_rcp_f32_e32 v167, v167
	v_rcp_f32_e32 v168, v168
	v_rcp_f32_e32 v169, v169
	v_pk_mul_f32 v[20:21], v[20:21], v[162:163]
	v_pk_mul_f32 v[22:23], v[22:23], v[164:165]
	v_pk_mul_f32 v[16:17], v[16:17], v[166:167]
	v_pk_mul_f32 v[18:19], v[18:19], v[168:169]
	v_cvt_pk_bf16_f32 v170, v20, v21
	v_cvt_pk_bf16_f32 v171, v22, v23
	v_cvt_pk_bf16_f32 v172, v16, v17
	v_cvt_pk_bf16_f32 v173, v18, v19
	global_store_dwordx4 v[160:161], v[170:173], off
	v_lshl_add_u64 v[160:161], v[160:161], 0, s[66:67]
	v_rsq_f32_e32 v176, v248
	v_pk_mul_f32 v[4:5], v[12:13], v[4:5]
	v_pk_mul_f32 v[6:7], v[14:15], v[6:7]
	v_pk_mul_f32 v[0:1], v[8:9], v[0:1]
	v_pk_mul_f32 v[2:3], v[10:11], v[2:3]
	v_mul_f32_e32 v177, 0xbfb8aa3b, v176
	v_mul_f32_e32 v162, v177, v12
	v_mul_f32_e32 v163, v177, v13
	v_mul_f32_e32 v164, v177, v14
	v_mul_f32_e32 v165, v177, v15
	v_mul_f32_e32 v166, v177, v8
	v_mul_f32_e32 v167, v177, v9
	v_mul_f32_e32 v168, v177, v10
	v_mul_f32_e32 v169, v177, v11
	v_exp_f32_e32 v162, v162
	v_exp_f32_e32 v163, v163
	v_exp_f32_e32 v164, v164
	v_exp_f32_e32 v165, v165
	v_exp_f32_e32 v166, v166
	v_exp_f32_e32 v167, v167
	v_exp_f32_e32 v168, v168
	v_exp_f32_e32 v169, v169
	v_fma_f32 v162, v162, v248, v248
	v_fma_f32 v163, v163, v248, v248
	v_fma_f32 v164, v164, v248, v248
	v_fma_f32 v165, v165, v248, v248
	v_fma_f32 v166, v166, v248, v248
	v_fma_f32 v167, v167, v248, v248
	v_fma_f32 v168, v168, v248, v248
	v_fma_f32 v169, v169, v248, v248
	v_rcp_f32_e32 v162, v162
	v_rcp_f32_e32 v163, v163
	v_rcp_f32_e32 v164, v164
	v_rcp_f32_e32 v165, v165
	v_rcp_f32_e32 v166, v166
	v_rcp_f32_e32 v167, v167
	v_rcp_f32_e32 v168, v168
	v_rcp_f32_e32 v169, v169
	v_pk_mul_f32 v[4:5], v[4:5], v[162:163]
	v_pk_mul_f32 v[6:7], v[6:7], v[164:165]
	v_pk_mul_f32 v[0:1], v[0:1], v[166:167]
	v_pk_mul_f32 v[2:3], v[2:3], v[168:169]
	v_cvt_pk_bf16_f32 v170, v4, v5
	v_cvt_pk_bf16_f32 v171, v6, v7
	v_cvt_pk_bf16_f32 v172, v0, v1
	v_cvt_pk_bf16_f32 v173, v2, v3
	global_store_dwordx4 v[160:161], v[170:173], off
	s_setprio 0
	s_cbranch_vccnz .LBB0_789
	s_branch .LBB0_788
